# pipelined residual epilogues + HGRN2 state-fold loads issued together + counted wait at HGRN2 chunk start
# speedup vs baseline: 1.0113x; 1.0113x over previous
.LBB0_729:
	v_lshl_add_u64 v[48:49], v[2:3], 0, s[0:1]
	s_mov_b32 s4, 0x6402000
	v_add_co_u32_e32 v40, vcc, s4, v48
	s_mov_b32 s4, 0x6400000
	s_nop 0
	v_addc_co_u32_e32 v41, vcc, 0, v49, vcc
	v_add_co_u32_e32 v52, vcc, s4, v48
	s_mov_b32 s4, 0x6401000
	s_nop 0
	v_addc_co_u32_e32 v53, vcc, 0, v49, vcc
	v_add_co_u32_e32 v54, vcc, s4, v48
	global_load_dwordx4 v[40:43], v[40:41], off
	s_nop 0
	v_addc_co_u32_e32 v55, vcc, 0, v49, vcc
	global_load_dwordx4 v[48:51], v[54:55], off offset:-4096
	global_load_dwordx4 v[76:79], v[52:53], off offset:1024
	global_load_dwordx4 v[80:83], v[52:53], off offset:2048
	global_load_dwordx4 v[84:87], v[52:53], off offset:3072
	global_load_dwordx4 v[88:91], v[54:55], off
	global_load_dwordx4 v[92:95], v[54:55], off offset:1024
	global_load_dwordx4 v[168:171], v[54:55], off offset:2048
	global_load_dwordx4 v[172:175], v[54:55], off offset:3072
	s_add_u32 s0, s0, 0x12000
	s_addc_u32 s1, s1, 0
	s_mul_i32 s4, s55, 0x12000
	s_cmp_eq_u32 s4, s0
	s_waitcnt vmcnt(7)
	v_pk_fma_f32 v[62:63], v[62:63], v[42:43], v[50:51]
	v_pk_fma_f32 v[60:61], v[60:61], v[40:41], v[48:49]
	s_waitcnt vmcnt(6)
	v_pk_fma_f32 v[70:71], v[70:71], v[42:43], v[78:79]
	v_pk_fma_f32 v[68:69], v[68:69], v[40:41], v[76:77]
	s_waitcnt vmcnt(5)
	v_pk_fma_f32 v[46:47], v[46:47], v[42:43], v[82:83]
	v_pk_fma_f32 v[44:45], v[44:45], v[40:41], v[80:81]
	s_waitcnt vmcnt(4)
	v_pk_fma_f32 v[38:39], v[38:39], v[42:43], v[86:87]
	v_pk_fma_f32 v[36:37], v[36:37], v[40:41], v[84:85]
	s_waitcnt vmcnt(3)
	v_pk_fma_f32 v[30:31], v[30:31], v[42:43], v[90:91]
	v_pk_fma_f32 v[28:29], v[28:29], v[40:41], v[88:89]
	s_waitcnt vmcnt(2)
	v_pk_fma_f32 v[26:27], v[26:27], v[42:43], v[94:95]
	v_pk_fma_f32 v[24:25], v[24:25], v[40:41], v[92:93]
	s_waitcnt vmcnt(1)
	v_pk_fma_f32 v[22:23], v[22:23], v[42:43], v[170:171]
	v_pk_fma_f32 v[20:21], v[20:21], v[40:41], v[168:169]
	s_waitcnt vmcnt(0)
	v_pk_fma_f32 v[18:19], v[18:19], v[42:43], v[174:175]
	v_pk_fma_f32 v[16:17], v[16:17], v[40:41], v[172:173]
	s_cbranch_scc0 .LBB0_729
	s_branch .LBB0_731

.LBB0_733:
	s_add_i32 s62, s72, s73
	s_cmp_ge_u32 s62, s71
	s_cselect_b64 s[12:13], -1, 0
	s_cmp_lt_u32 s62, s71
	s_cbranch_scc1 .LBB0_735
	v_lshl_add_u64 v[4:5], v[140:141], 0, s[4:5]
	s_mov_b64 s[54:55], 0xa401800
	v_lshl_add_u64 v[8:9], v[4:5], 0, s[54:55]
	v_add_co_u32_e32 v4, vcc, 0xa401000, v4
	s_nop 1
	v_addc_co_u32_e32 v5, vcc, 0, v5, vcc
	global_load_dwordx4 v[4:7], v[4:5], off offset:2048
	s_nop 0
	global_load_dwordx4 v[8:11], v[8:9], off offset:16
	s_waitcnt vmcnt(2)
	s_branch .Lhg1_chunk_go

.Lhg1_chunk_go:
	v_and_b32_e32 v84, 0xffff, v76
	v_lshrrev_b32_e32 v85, 16, v76
	v_lshl_or_b32 v84, v80, 16, v84
	v_and_or_b32 v85, v80, s64, v85
	v_add_u32_e32 v231, 0xd000, v192
	ds_write2_b32 v231, v84, v85 offset1:36
	v_and_b32_e32 v84, 0xffff, v77
	v_lshrrev_b32_e32 v85, 16, v77
	v_lshl_or_b32 v84, v81, 16, v84
	v_and_or_b32 v85, v81, s64, v85
	ds_write2_b32 v231, v84, v85 offset0:72 offset1:108
	v_and_b32_e32 v84, 0xffff, v78
	v_lshrrev_b32_e32 v85, 16, v78
	v_cvt_f32_f16_sdwa v167, v223 dst_sel:DWORD dst_unused:UNUSED_PAD src0_sel:WORD_1
	v_cvt_f32_f16_e32 v166, v223
	v_cvt_f32_f16_sdwa v99, v224 dst_sel:DWORD dst_unused:UNUSED_PAD src0_sel:WORD_1
	v_cvt_f32_f16_e32 v98, v224
	v_lshl_or_b32 v84, v82, 16, v84
	v_and_or_b32 v85, v82, s64, v85
	v_cvt_f32_f16_sdwa v145, v225 dst_sel:DWORD dst_unused:UNUSED_PAD src0_sel:WORD_1
	v_cvt_f32_f16_e32 v144, v225
	ds_write2_b32 v231, v84, v85 offset0:144 offset1:180
	v_and_b32_e32 v84, 0xffff, v79
	v_lshrrev_b32_e32 v85, 16, v79
	v_cvt_f32_f16_sdwa v147, v226 dst_sel:DWORD dst_unused:UNUSED_PAD src0_sel:WORD_1
	v_cvt_f32_f16_e32 v146, v226
	v_lshl_or_b32 v84, v83, 16, v84
	v_and_or_b32 v85, v83, s64, v85
	v_cvt_f32_f16_sdwa v101, v227 dst_sel:DWORD dst_unused:UNUSED_PAD src0_sel:WORD_1
	v_cvt_f32_f16_e32 v100, v227
	ds_write2_b32 v231, v84, v85 offset0:216 offset1:252
	v_cvt_f32_f16_sdwa v95, v228 dst_sel:DWORD dst_unused:UNUSED_PAD src0_sel:WORD_1
	v_cvt_f32_f16_e32 v94, v228
	v_pk_add_f32 v[170:171], v[166:167], 1.0 op_sel_hi:[1,0] neg_lo:[1,0] neg_hi:[1,0]
	v_pk_add_f32 v[84:85], v[98:99], 1.0 op_sel_hi:[1,0] neg_lo:[1,0] neg_hi:[1,0]
	v_cvt_f32_f16_sdwa v91, v229 dst_sel:DWORD dst_unused:UNUSED_PAD src0_sel:WORD_1
	v_cvt_f32_f16_e32 v90, v229
	v_pk_mul_f32 v[168:169], v[170:171], v[84:85]
	v_pk_add_f32 v[84:85], v[144:145], 1.0 op_sel_hi:[1,0] neg_lo:[1,0] neg_hi:[1,0]
	v_cvt_f32_f16_sdwa v89, v230 dst_sel:DWORD dst_unused:UNUSED_PAD src0_sel:WORD_1
	v_cvt_f32_f16_e32 v88, v230
	v_pk_mul_f32 v[152:153], v[168:169], v[84:85]
	v_pk_add_f32 v[84:85], v[146:147], 1.0 op_sel_hi:[1,0] neg_lo:[1,0] neg_hi:[1,0]
	s_nop 0
	v_pk_mul_f32 v[150:151], v[152:153], v[84:85]
	v_pk_add_f32 v[84:85], v[100:101], 1.0 op_sel_hi:[1,0] neg_lo:[1,0] neg_hi:[1,0]
	s_nop 0
	v_pk_mul_f32 v[148:149], v[150:151], v[84:85]
	v_pk_add_f32 v[84:85], v[94:95], 1.0 op_sel_hi:[1,0] neg_lo:[1,0] neg_hi:[1,0]
	s_nop 0
	v_pk_mul_f32 v[102:103], v[148:149], v[84:85]
	v_pk_add_f32 v[84:85], v[90:91], 1.0 op_sel_hi:[1,0] neg_lo:[1,0] neg_hi:[1,0]
	s_nop 0
	v_pk_mul_f32 v[96:97], v[102:103], v[84:85]
	v_pk_add_f32 v[84:85], v[88:89], 1.0 op_sel_hi:[1,0] neg_lo:[1,0] neg_hi:[1,0]
	s_nop 0
	v_pk_mul_f32 v[92:93], v[96:97], v[84:85]
	ds_write_b64 v119, v[92:93]
	s_waitcnt lgkmcnt(0)
	s_barrier
	ds_read2st64_b64 v[84:87], v107 offset1:1
	ds_read2st64_b64 v[172:175], v107 offset0:2 offset1:3
	ds_read2st64_b64 v[232:235], v107 offset0:4 offset1:5
	ds_read2st64_b64 v[236:239], v107 offset0:6 offset1:7
	s_waitcnt lgkmcnt(3)
	v_pk_mul_f32 v[182:183], v[84:85], v[86:87]
	s_waitcnt lgkmcnt(2)
	v_pk_mul_f32 v[180:181], v[182:183], v[172:173]
	s_nop 0
	v_pk_mul_f32 v[178:179], v[180:181], v[174:175]
	s_waitcnt lgkmcnt(1)
	v_pk_mul_f32 v[176:177], v[178:179], v[232:233]
	s_nop 0
	v_pk_mul_f32 v[174:175], v[176:177], v[234:235]
	s_waitcnt lgkmcnt(0)
	v_pk_mul_f32 v[172:173], v[174:175], v[236:237]
	s_nop 0
	v_pk_mul_f32 v[86:87], v[172:173], v[238:239]
	s_and_saveexec_b64 s[54:55], s[14:15]
	ds_write_b64 v184, v[86:87]
	s_or_b64 exec, exec, s[54:55]
	v_cndmask_b32_e64 v84, 1.0, v84, s[18:19]
	v_cndmask_b32_e64 v85, 1.0, v85, s[18:19]
	v_cndmask_b32_e64 v84, v84, v182, s[20:21]
	v_cndmask_b32_e64 v85, v85, v183, s[20:21]
	v_cndmask_b32_e64 v84, v84, v180, s[22:23]
	v_cndmask_b32_e64 v85, v85, v181, s[22:23]
	v_cndmask_b32_e64 v84, v84, v178, s[24:25]
	v_cndmask_b32_e64 v85, v85, v179, s[24:25]
	v_cndmask_b32_e64 v84, v84, v176, s[26:27]
	v_cndmask_b32_e64 v85, v85, v177, s[26:27]
	v_cndmask_b32_e64 v84, v84, v174, s[28:29]
	v_cndmask_b32_e64 v85, v85, v175, s[28:29]
	v_cndmask_b32_e64 v172, v84, v172, s[30:31]
	v_cndmask_b32_e64 v137, v85, v173, s[30:31]
	v_mul_f32_e32 v84, v170, v172
	v_max_f32_e32 v170, 0xda24260, v84
	v_mul_f32_e32 v84, v171, v137
	v_max_f32_e32 v171, 0xda24260, v84
	v_rcp_f32_e32 v84, v170
	v_rcp_f32_e32 v85, v171
	s_and_b64 vcc, exec, s[12:13]
	v_pk_mul_f32 v[84:85], v[84:85], v[166:167]
	s_cbranch_vccz .LBB0_739
	v_lshlrev_b32_e32 v166, 16, v222
	v_and_b32_e32 v167, 0xffff0000, v222
	v_pk_mul_f32 v[166:167], v[170:171], v[166:167]
	s_nop 0
	v_cvt_pk_bf16_f32 v166, v166, v167
	v_cvt_pk_bf16_f32 v167, v84, v85
	ds_write2st64_b32 v124, v166, v167 offset1:68

.LBB0_753:
	v_mov_b32_e32 v92, v84
	v_mov_b32_e32 v93, v98
	v_pk_mul_f32 v[92:93], v[86:87], v[92:93] op_sel_hi:[0,1]
	v_cvt_pk_bf16_f32 v148, v92, v93
	v_mov_b32_e32 v92, v144
	v_mov_b32_e32 v93, v146
	v_pk_mul_f32 v[92:93], v[86:87], v[92:93] op_sel_hi:[0,1]
	v_cvt_pk_bf16_f32 v149, v92, v93
	v_mov_b32_e32 v92, v100
	v_mov_b32_e32 v93, v94
	v_pk_mul_f32 v[92:93], v[86:87], v[92:93] op_sel_hi:[0,1]
	v_mov_b32_e32 v94, v101
	v_cvt_pk_bf16_f32 v150, v92, v93
	v_pk_mul_f32 v[92:93], v[86:87], v[94:95] op_sel:[1,0]
	v_mov_b32_e32 v146, v145
	v_mov_b32_e32 v98, v85
	v_cvt_pk_bf16_f32 v94, v92, v93
	v_pk_mul_f32 v[92:93], v[86:87], v[146:147] op_sel:[1,0]
	v_pk_mul_f32 v[84:85], v[86:87], v[98:99] op_sel:[1,0]
	v_cvt_pk_bf16_f32 v93, v92, v93
	v_cvt_pk_bf16_f32 v92, v84, v85
	v_mov_b32_e32 v84, v90
	v_mov_b32_e32 v85, v88
	v_pk_mul_f32 v[84:85], v[86:87], v[84:85] op_sel_hi:[0,1]
	v_mov_b32_e32 v88, v91
	v_cvt_pk_bf16_f32 v151, v84, v85
	v_pk_mul_f32 v[84:85], v[86:87], v[88:89] op_sel:[1,0]
	s_add_i32 s62, s62, 1
	v_cvt_pk_bf16_f32 v95, v84, v85
	ds_write_b128 v185, v[148:151] offset:34816
	ds_write_b128 v185, v[92:95] offset:34960
	s_waitcnt vmcnt(0)
	s_waitcnt lgkmcnt(0)
	s_barrier
	s_cmp_lt_u32 s62, s61
	s_cbranch_scc0 .LBB0_756
	v_lshl_add_u64 v[84:85], v[138:139], 0, s[4:5]
	v_add_co_u32_e32 v76, vcc, 0xa480000, v84
	v_lshl_add_u64 v[80:81], v[2:3], 0, s[4:5]
	s_nop 0
	v_addc_co_u32_e32 v77, vcc, 0, v85, vcc
	global_load_dword v223, v[76:77], off offset:2048
	v_add_co_u32_e32 v76, vcc, 0xa482000, v84
	s_cmp_ge_u32 s62, s71
	s_nop 0
	v_addc_co_u32_e32 v77, vcc, 0, v85, vcc
	global_load_dword v224, v[76:77], off offset:2048
	v_add_co_u32_e32 v76, vcc, 0xa484000, v84
	s_nop 1
	v_addc_co_u32_e32 v77, vcc, 0, v85, vcc
	global_load_dword v225, v[76:77], off offset:2048
	v_add_co_u32_e32 v76, vcc, 0xa486000, v84
	s_nop 1
	v_addc_co_u32_e32 v77, vcc, 0, v85, vcc
	global_load_dword v226, v[76:77], off offset:2048
	v_add_co_u32_e32 v76, vcc, 0xa488000, v84
	s_nop 1
	v_addc_co_u32_e32 v77, vcc, 0, v85, vcc
	global_load_dword v227, v[76:77], off offset:2048
	v_add_co_u32_e32 v76, vcc, 0xa48a000, v84
	s_nop 1
	v_addc_co_u32_e32 v77, vcc, 0, v85, vcc
	global_load_dword v228, v[76:77], off offset:2048
	v_add_co_u32_e32 v76, vcc, 0xa48c000, v84
	s_nop 1
	v_addc_co_u32_e32 v77, vcc, 0, v85, vcc
	global_load_dword v229, v[76:77], off offset:2048
	v_add_co_u32_e32 v76, vcc, 0xa48e000, v84
	s_nop 1
	v_addc_co_u32_e32 v77, vcc, 0, v85, vcc
	global_load_dword v230, v[76:77], off offset:2048
	v_add_co_u32_e32 v76, vcc, 0xa481000, v80
	s_nop 1
	v_addc_co_u32_e32 v77, vcc, 0, v81, vcc
	v_add_co_u32_e32 v80, vcc, 0xa483000, v80
	global_load_dwordx4 v[76:79], v[76:77], off
	s_nop 0
	v_addc_co_u32_e32 v81, vcc, 0, v81, vcc
	global_load_dwordx4 v[80:83], v[80:81], off
	s_cbranch_scc0 .LBB0_756
	v_add_co_u32_e32 v86, vcc, 0xa480000, v84
	s_nop 1
	v_addc_co_u32_e32 v87, vcc, 0, v85, vcc
	global_load_dword v222, v[86:87], off
	v_add_co_u32_e32 v86, vcc, 0xa482000, v84
	s_nop 1
	v_addc_co_u32_e32 v87, vcc, 0, v85, vcc
	global_load_dword v221, v[86:87], off
	v_add_co_u32_e32 v86, vcc, 0xa484000, v84
	s_nop 1
	v_addc_co_u32_e32 v87, vcc, 0, v85, vcc
	global_load_dword v220, v[86:87], off
	v_add_co_u32_e32 v86, vcc, 0xa486000, v84
	s_nop 1
	v_addc_co_u32_e32 v87, vcc, 0, v85, vcc
	global_load_dword v219, v[86:87], off
	v_add_co_u32_e32 v86, vcc, 0xa488000, v84
	s_nop 1
	v_addc_co_u32_e32 v87, vcc, 0, v85, vcc
	global_load_dword v218, v[86:87], off
	v_add_co_u32_e32 v86, vcc, 0xa48a000, v84
	s_nop 1
	v_addc_co_u32_e32 v87, vcc, 0, v85, vcc
	global_load_dword v217, v[86:87], off
	v_add_co_u32_e32 v86, vcc, 0xa48c000, v84
	s_nop 1
	v_addc_co_u32_e32 v87, vcc, 0, v85, vcc
	v_add_co_u32_e32 v84, vcc, 0xa48e000, v84
	global_load_dword v0, v[86:87], off
	s_nop 0
	v_addc_co_u32_e32 v85, vcc, 0, v85, vcc
	global_load_dword v135, v[84:85], off
